# seams: the XCC leader issues its XGEN release add without first waiting for the cross-XCC generation add to complete (4 more seams)
# speedup vs baseline: 1.0035x; 1.0035x over previous
; __device__ __forceinline__ unsigned xb_ld(unsigned* p)              { return __hip_atomic_load(p, __ATOMIC_RELAXED, __HIP_MEMORY_SCOPE_AGENT); }
; __device__ __forceinline__ unsigned xb_add(unsigned* p, unsigned v) { return __hip_atomic_fetch_add(p, v, __ATOMIC_RELAXED, __HIP_MEMORY_SCOPE_AGENT); }
; #define XB_SPIN(cond, bar) do { unsigned _sp = 0; while (cond) { __builtin_amdgcn_s_sleep(1); \
;     if ((++_sp & 255u) == 0u) { if (xb_ld(&(bar)[XB_TMO])) break; if (_sp > XB_SPIN_CAP) { atomicAdd(&(bar)[XB_TMO], 1u); break; } } } } while (0)
; __device__ __forceinline__ void xcd_barrier(const XcdBarrier& b) {
;     ...
;             __builtin_amdgcn_fence(__ATOMIC_RELEASE, "agent");
;             asm volatile("s_waitcnt vmcnt(0)" ::: "memory");
;             const unsigned og = xb_add(&bar[XB_TOP], 1u);
;             const unsigned tg = og / nx;
;             if (og + 1u == (tg + 1u) * nx) xb_add(&bar[XB_TOPGEN], 1u);
;             else XB_SPIN(xb_ld(&bar[XB_TOPGEN]) == tg, bar);
;             __builtin_amdgcn_fence(__ATOMIC_ACQUIRE, "agent");
;             xb_add(&bar[XB_XGEN(b.x)], 1u);
;             asm volatile("s_waitcnt vmcnt(0)" ::: "memory");
.LBB0_256:
	s_or_b64 exec, exec, s[42:43]
	s_mov_b64 s[42:43], exec
	v_mbcnt_lo_u32_b32 v0, s42, 0
	v_mbcnt_hi_u32_b32 v0, s43, v0
	v_cmp_eq_u32_e32 vcc, 0, v0
	s_nop 0
	s_and_saveexec_b64 s[44:45], vcc
	s_cbranch_execz .LBB0_258
	s_bcnt1_i32_b64 s3, s[42:43]
	v_readlane_b32 s12, v255, 10
	v_mov_b32_e32 v0, s3
	v_readlane_b32 s13, v255, 11
	s_nop 4
	global_atomic_add v1, v0, s[12:13]

; __device__ __forceinline__ unsigned xb_ld(unsigned* p)              { return __hip_atomic_load(p, __ATOMIC_RELAXED, __HIP_MEMORY_SCOPE_AGENT); }
; __device__ __forceinline__ unsigned xb_add(unsigned* p, unsigned v) { return __hip_atomic_fetch_add(p, v, __ATOMIC_RELAXED, __HIP_MEMORY_SCOPE_AGENT); }
; #define XB_SPIN(cond, bar) do { unsigned _sp = 0; while (cond) { __builtin_amdgcn_s_sleep(1); \
;     if ((++_sp & 255u) == 0u) { if (xb_ld(&(bar)[XB_TMO])) break; if (_sp > XB_SPIN_CAP) { atomicAdd(&(bar)[XB_TMO], 1u); break; } } } } while (0)
; __device__ __forceinline__ void xcd_barrier(const XcdBarrier& b) {
;     ...
;             __builtin_amdgcn_fence(__ATOMIC_RELEASE, "agent");
;             asm volatile("s_waitcnt vmcnt(0)" ::: "memory");
;             const unsigned og = xb_add(&bar[XB_TOP], 1u);
;             const unsigned tg = og / nx;
;             if (og + 1u == (tg + 1u) * nx) xb_add(&bar[XB_TOPGEN], 1u);
;             else XB_SPIN(xb_ld(&bar[XB_TOPGEN]) == tg, bar);
;             __builtin_amdgcn_fence(__ATOMIC_ACQUIRE, "agent");
;             xb_add(&bar[XB_XGEN(b.x)], 1u);
;             asm volatile("s_waitcnt vmcnt(0)" ::: "memory");
.LBB0_333:
	s_or_b64 exec, exec, s[38:39]
	s_mov_b64 s[38:39], exec
	v_mbcnt_lo_u32_b32 v0, s38, 0
	v_mbcnt_hi_u32_b32 v0, s39, v0
	v_cmp_eq_u32_e32 vcc, 0, v0
	s_nop 0
	s_and_saveexec_b64 s[40:41], vcc
	s_cbranch_execz .LBB0_335
	s_bcnt1_i32_b64 s12, s[38:39]
	v_mov_b32_e32 v0, s12
	v_readlane_b32 s12, v255, 10
	v_readlane_b32 s13, v255, 11
	s_nop 4
	global_atomic_add v1, v0, s[12:13]

; __device__ __forceinline__ unsigned xb_ld(unsigned* p)              { return __hip_atomic_load(p, __ATOMIC_RELAXED, __HIP_MEMORY_SCOPE_AGENT); }
; __device__ __forceinline__ unsigned xb_add(unsigned* p, unsigned v) { return __hip_atomic_fetch_add(p, v, __ATOMIC_RELAXED, __HIP_MEMORY_SCOPE_AGENT); }
; #define XB_SPIN(cond, bar) do { unsigned _sp = 0; while (cond) { __builtin_amdgcn_s_sleep(1); \
;     if ((++_sp & 255u) == 0u) { if (xb_ld(&(bar)[XB_TMO])) break; if (_sp > XB_SPIN_CAP) { atomicAdd(&(bar)[XB_TMO], 1u); break; } } } } while (0)
; __device__ __forceinline__ void xcd_barrier(const XcdBarrier& b) {
;     ...
;             __builtin_amdgcn_fence(__ATOMIC_RELEASE, "agent");
;             asm volatile("s_waitcnt vmcnt(0)" ::: "memory");
;             const unsigned og = xb_add(&bar[XB_TOP], 1u);
;             const unsigned tg = og / nx;
;             if (og + 1u == (tg + 1u) * nx) xb_add(&bar[XB_TOPGEN], 1u);
;             else XB_SPIN(xb_ld(&bar[XB_TOPGEN]) == tg, bar);
;             __builtin_amdgcn_fence(__ATOMIC_ACQUIRE, "agent");
;             xb_add(&bar[XB_XGEN(b.x)], 1u);
;             asm volatile("s_waitcnt vmcnt(0)" ::: "memory");
.LBB0_507:
	s_or_b64 exec, exec, s[38:39]
	s_mov_b64 s[38:39], exec
	v_mbcnt_lo_u32_b32 v0, s38, 0
	v_mbcnt_hi_u32_b32 v0, s39, v0
	v_cmp_eq_u32_e32 vcc, 0, v0
	s_nop 0
	s_and_saveexec_b64 s[40:41], vcc
	s_cbranch_execz .LBB0_509
	s_bcnt1_i32_b64 s3, s[38:39]
	v_readlane_b32 s12, v255, 10
	v_mov_b32_e32 v0, s3
	v_readlane_b32 s13, v255, 11
	s_nop 4
	global_atomic_add v1, v0, s[12:13]

; __device__ __forceinline__ unsigned xb_ld(unsigned* p)              { return __hip_atomic_load(p, __ATOMIC_RELAXED, __HIP_MEMORY_SCOPE_AGENT); }
; __device__ __forceinline__ unsigned xb_add(unsigned* p, unsigned v) { return __hip_atomic_fetch_add(p, v, __ATOMIC_RELAXED, __HIP_MEMORY_SCOPE_AGENT); }
; #define XB_SPIN(cond, bar) do { unsigned _sp = 0; while (cond) { __builtin_amdgcn_s_sleep(1); \
;     if ((++_sp & 255u) == 0u) { if (xb_ld(&(bar)[XB_TMO])) break; if (_sp > XB_SPIN_CAP) { atomicAdd(&(bar)[XB_TMO], 1u); break; } } } } while (0)
; __device__ __forceinline__ void xcd_barrier(const XcdBarrier& b) {
;     ...
;             __builtin_amdgcn_fence(__ATOMIC_RELEASE, "agent");
;             asm volatile("s_waitcnt vmcnt(0)" ::: "memory");
;             const unsigned og = xb_add(&bar[XB_TOP], 1u);
;             const unsigned tg = og / nx;
;             if (og + 1u == (tg + 1u) * nx) xb_add(&bar[XB_TOPGEN], 1u);
;             else XB_SPIN(xb_ld(&bar[XB_TOPGEN]) == tg, bar);
;             __builtin_amdgcn_fence(__ATOMIC_ACQUIRE, "agent");
;             xb_add(&bar[XB_XGEN(b.x)], 1u);
;             asm volatile("s_waitcnt vmcnt(0)" ::: "memory");
.LBB0_652:
	s_or_b64 exec, exec, s[38:39]
	s_mov_b64 s[38:39], exec
	v_mbcnt_lo_u32_b32 v0, s38, 0
	v_mbcnt_hi_u32_b32 v0, s39, v0
	v_cmp_eq_u32_e32 vcc, 0, v0
	s_nop 0
	s_and_saveexec_b64 s[40:41], vcc
	s_cbranch_execz .LBB0_654
	s_bcnt1_i32_b64 s6, s[38:39]
	v_readlane_b32 s12, v255, 10
	v_mov_b32_e32 v0, s6
	v_readlane_b32 s13, v255, 11
	s_nop 4
	global_atomic_add v1, v0, s[12:13]
.LBB0_654:
	s_or_b64 exec, exec, s[40:41]
	buffer_inv sc1
	s_waitcnt vmcnt(0)
